# global seams 4,5: slot-based local arrival, fixed leader per XCC, cross-XCD exchange through one line of write-through slots, L2-flag release, early L1/L2 invalidate on wave 1
# speedup vs baseline: 1.0028x; 1.0023x over previous
.LBB0_782:
	s_cmp_gt_i32 s69, 5
	s_cselect_b64 s[0:1], -1, 0
	s_and_b64 s[2:3], s[18:19], s[0:1]
	s_andn2_b64 vcc, exec, s[2:3]
	s_cbranch_vccnz .LBB0_836
	s_waitcnt vmcnt(0)
	s_waitcnt vmcnt(0) lgkmcnt(0)
	s_barrier
	v_mov_b32_e32 v0, 0x20040
	ds_read_b32 v2, v0
	ds_read_b32 v3, v0 offset:16
	ds_read_b32 v5, v0 offset:8
	s_lshl_b32 s2, s33, 8
	s_add_u32 s2, s2, 0x1480
	v_lshl_add_u32 v0, v199, 2, s2
	v_and_b32_e32 v7, 7, v199
	v_lshlrev_b32_e32 v7, 2, v7
	v_add_u32_e32 v7, 0x3480, v7
	v_mov_b32_e32 v9, s33
	v_lshlrev_b32_e32 v9, 2, v9
	v_add_u32_e32 v9, 0x3480, v9
	v_mov_b32_e32 v8, s2
	v_mov_b32_e32 v6, 1
	s_waitcnt lgkmcnt(0)
	v_cmp_eq_u32_e32 vcc, 0, v3
	s_cbranch_vccnz .Lxg_orig_4
	v_cmp_lt_u32_e32 vcc, 32, v2
	s_cbranch_vccnz .Lxg_orig_4
	v_lshl_add_u32 v1, v5, 2, s2
	v_readfirstlane_b32 s3, v199
	s_nop 3
	s_cmp_eq_u32 s3, 64
	s_cbranch_scc0 .Lxg_noinv_4
	buffer_inv sc1
	s_waitcnt vmcnt(0)
.Lxg_noinv_4:
	v_readfirstlane_b32 s3, v5
	v_cmp_lt_u32_e32 vcc, v199, v2
	s_and_saveexec_b64 s[4:5], vcc
	s_cbranch_execz .LBB0_835
	global_store_dword v1, v6, s[92:93]
	s_mov_b32 s2, 0x8000
	s_cmp_lg_u32 s3, 0
	s_cbranch_scc1 .Lxg_rel_4

.Lxg_all_4:
	buffer_wbl2 sc1
	s_waitcnt vmcnt(0)
	global_store_dword v9, v6, s[92:93] sc0 sc1
	s_mov_b32 s2, 0x8000
.Lxg_top_4:
	global_load_dword v4, v7, s[92:93] sc0 sc1
	s_waitcnt vmcnt(0)
	v_cmp_gt_u32_e32 vcc, 1, v4
	s_cbranch_vccz .Lxg_topdone_4
	s_sleep 1
	s_sub_u32 s2, s2, 1
	s_cmp_lg_u32 s2, 0
	s_cbranch_scc1 .Lxg_top_4
.Lxg_topdone_4:
	global_store_dword v8, v6, s[92:93] offset:-4096
	buffer_inv sc1
	s_waitcnt vmcnt(0)
	s_branch .LBB0_835
.Lxg_rel_4:
	global_load_dword v4, v8, s[92:93] offset:-4096 sc1
	s_waitcnt vmcnt(0)
	v_cmp_gt_u32_e32 vcc, 1, v4
	s_cbranch_vccz .LBB0_835
	s_sleep 1
	s_sub_u32 s2, s2, 1
	s_cmp_lg_u32 s2, 0
	s_cbranch_scc1 .Lxg_rel_4
	s_branch .LBB0_835
.Lxg_orig_4:
	s_mov_b64 s[4:5], exec
	v_readlane_b32 s2, v255, 1
	v_readlane_b32 s3, v255, 2
	s_and_b64 s[2:3], s[4:5], s[2:3]
	s_mov_b64 exec, s[2:3]
	s_cbranch_execz .LBB0_835
	s_add_i32 s2, 0, 0x20040
	v_mov_b32_e32 v0, s2
	s_waitcnt vmcnt(0) expcnt(0) lgkmcnt(0)
	ds_read_b32 v2, v0
	s_add_i32 s2, 0, 0x20044
	v_mov_b32_e32 v0, s2
	ds_read_b32 v0, v0
	s_waitcnt lgkmcnt(1)
	v_cmp_ne_u32_e32 vcc, 0, v2
	s_cbranch_vccnz .LBB0_799
	s_add_u32 s6, s30, 0xfc00200
	s_addc_u32 s7, s31, 0
	s_add_u32 s8, s30, 0xfc00400
	s_addc_u32 s9, s31, 0
	s_add_u32 s12, s30, 0xfc00500
	s_addc_u32 s13, s31, 0
	s_add_u32 s18, s30, 0xfc00600
	s_addc_u32 s19, s31, 0
	s_add_u32 s20, s30, 0xfc00700
	s_addc_u32 s21, s31, 0
	s_add_u32 s24, s30, 0xfc00800
	s_addc_u32 s25, s31, 0
	s_add_u32 s26, s30, 0xfc00900
	s_addc_u32 s27, s31, 0
	s_add_u32 s42, s30, 0xfc00a00
	s_addc_u32 s43, s31, 0
	s_add_u32 s46, s30, 0xfc00b00
	s_addc_u32 s47, s31, 0
	s_add_u32 s48, s30, 0xfc00c00
	s_addc_u32 s49, s31, 0
	s_add_u32 s50, s30, 0xfc00d00
	s_addc_u32 s51, s31, 0
	s_add_u32 s52, s30, 0xfc00e00
	s_addc_u32 s53, s31, 0
	s_add_u32 s54, s30, 0xfc00f00
	s_addc_u32 s55, s31, 0
	s_add_u32 s56, s30, 0xfc01000
	s_addc_u32 s57, s31, 0
	s_add_u32 s58, s30, 0xfc01100
	s_addc_u32 s59, s31, 0
	s_add_u32 s60, s30, 0xfc01200
	v_readlane_b32 s2, v255, 0
	s_addc_u32 s61, s31, 0
	s_mul_i32 s2, s35, s2
	s_add_u32 s62, s30, 0xfc01300
	s_mul_i32 s2, s2, s34
	s_addc_u32 s63, s31, 0
	s_mov_b32 s3, 1
	v_mov_b32_e32 v16, 0
	s_branch .LBB0_787

.LBB0_1399:
	s_cmp_gt_i32 s69, 6
	s_cselect_b64 s[0:1], -1, 0
	s_and_b64 s[2:3], s[4:5], s[0:1]
	s_andn2_b64 vcc, exec, s[2:3]
	s_cbranch_vccnz .LBB0_1453
	s_waitcnt vmcnt(0)
	s_waitcnt vmcnt(0) lgkmcnt(0)
	s_barrier
	v_mov_b32_e32 v0, 0x20040
	ds_read_b32 v2, v0
	ds_read_b32 v3, v0 offset:16
	ds_read_b32 v5, v0 offset:8
	s_lshl_b32 s4, s33, 8
	s_add_u32 s4, s4, 0x1480
	v_lshl_add_u32 v0, v199, 2, s4
	v_and_b32_e32 v7, 7, v199
	v_lshlrev_b32_e32 v7, 2, v7
	v_add_u32_e32 v7, 0x3480, v7
	v_mov_b32_e32 v9, s33
	v_lshlrev_b32_e32 v9, 2, v9
	v_add_u32_e32 v9, 0x3480, v9
	v_mov_b32_e32 v8, s4
	v_mov_b32_e32 v6, 2
	s_waitcnt lgkmcnt(0)
	v_cmp_eq_u32_e32 vcc, 0, v3
	s_cbranch_vccnz .Lxg_orig_5
	v_cmp_lt_u32_e32 vcc, 32, v2
	s_cbranch_vccnz .Lxg_orig_5
	v_lshl_add_u32 v1, v5, 2, s4
	v_readfirstlane_b32 s5, v199
	s_nop 3
	s_cmp_eq_u32 s5, 64
	s_cbranch_scc0 .Lxg_noinv_5
	buffer_inv sc1
	s_waitcnt vmcnt(0)
.Lxg_noinv_5:
	v_readfirstlane_b32 s5, v5
	v_cmp_lt_u32_e32 vcc, v199, v2
	s_and_saveexec_b64 s[2:3], vcc
	s_cbranch_execz .LBB0_1452
	global_store_dword v1, v6, s[92:93]
	s_mov_b32 s4, 0x8000
	s_cmp_lg_u32 s5, 0
	s_cbranch_scc1 .Lxg_rel_5
.Lxg_arr_5:
	global_load_dword v4, v0, s[92:93] sc1
	s_waitcnt vmcnt(0)
	v_cmp_gt_u32_e32 vcc, 2, v4
	s_cbranch_vccz .Lxg_all_5
	s_sleep 1
	s_sub_u32 s4, s4, 1
	s_cmp_lg_u32 s4, 0
	s_cbranch_scc1 .Lxg_arr_5
.Lxg_all_5:
	buffer_wbl2 sc1
	s_waitcnt vmcnt(0)
	global_store_dword v9, v6, s[92:93] sc0 sc1
	s_mov_b32 s4, 0x8000
.Lxg_top_5:
	global_load_dword v4, v7, s[92:93] sc0 sc1
	s_waitcnt vmcnt(0)
	v_cmp_gt_u32_e32 vcc, 2, v4
	s_cbranch_vccz .Lxg_topdone_5
	s_sleep 1
	s_sub_u32 s4, s4, 1
	s_cmp_lg_u32 s4, 0
	s_cbranch_scc1 .Lxg_top_5

.Lxg_rel_5:
	global_load_dword v4, v8, s[92:93] offset:-4096 sc1
	s_waitcnt vmcnt(0)
	v_cmp_gt_u32_e32 vcc, 2, v4
	s_cbranch_vccz .LBB0_1452
	s_sleep 1
	s_sub_u32 s4, s4, 1
	s_cmp_lg_u32 s4, 0
	s_cbranch_scc1 .Lxg_rel_5
	s_branch .LBB0_1452
.Lxg_orig_5:
	s_mov_b64 s[2:3], exec
	v_readlane_b32 s4, v255, 1
	v_readlane_b32 s5, v255, 2
	s_and_b64 s[4:5], s[2:3], s[4:5]
	s_mov_b64 exec, s[4:5]
	s_cbranch_execz .LBB0_1452
	s_add_i32 s4, 0, 0x20040
	v_mov_b32_e32 v0, s4
	s_waitcnt vmcnt(0) expcnt(0) lgkmcnt(0)
	ds_read_b32 v2, v0
	s_add_i32 s4, 0, 0x20044
	v_mov_b32_e32 v0, s4
	ds_read_b32 v0, v0
	s_waitcnt lgkmcnt(1)
	v_cmp_ne_u32_e32 vcc, 0, v2
	s_cbranch_vccnz .LBB0_1416
	v_readlane_b32 s4, v255, 0
	s_mul_i32 s16, s35, s4
	s_add_u32 s4, s30, 0xfc00200
	s_addc_u32 s5, s31, 0
	s_add_u32 s6, s30, 0xfc00400
	s_addc_u32 s7, s31, 0
	s_add_u32 s8, s30, 0xfc00500
	s_addc_u32 s9, s31, 0
	s_add_u32 s12, s30, 0xfc00600
	s_addc_u32 s13, s31, 0
	s_add_u32 s14, s30, 0xfc00700
	s_addc_u32 s15, s31, 0
	s_add_u32 s18, s30, 0xfc00800
	s_addc_u32 s19, s31, 0
	s_add_u32 s20, s30, 0xfc00900
	s_addc_u32 s21, s31, 0
	s_add_u32 s24, s30, 0xfc00a00
	s_addc_u32 s25, s31, 0
	s_add_u32 s26, s30, 0xfc00b00
	s_addc_u32 s27, s31, 0
	s_add_u32 s42, s30, 0xfc00c00
	s_addc_u32 s43, s31, 0
	s_add_u32 s44, s30, 0xfc00d00
	s_addc_u32 s45, s31, 0
	s_add_u32 s46, s30, 0xfc00e00
	s_addc_u32 s47, s31, 0
	s_add_u32 s48, s30, 0xfc00f00
	s_addc_u32 s49, s31, 0
	s_add_u32 s50, s30, 0xfc01000
	s_addc_u32 s51, s31, 0
	s_add_u32 s52, s30, 0xfc01100
	s_addc_u32 s53, s31, 0
	s_add_u32 s54, s30, 0xfc01200
	s_addc_u32 s55, s31, 0
	s_add_u32 s56, s30, 0xfc01300
	s_mul_i32 s16, s16, s34
	s_addc_u32 s57, s31, 0
	s_mov_b32 s17, 1
	v_mov_b32_e32 v16, 0
	s_branch .LBB0_1404
